# hg_passB: the seven serial row sum-of-squares reductions (2 dependent ds_bpermute each) interleaved into two batched permute stages
# speedup vs baseline: 1.0026x; 1.0006x over previous
; __device__ __forceinline__ float shx(float v, int o, int lane) { return __builtin_bit_cast(float, __builtin_amdgcn_ds_bpermute((lane ^ o) << 2, __builtin_bit_cast(int, v))); }
; __device__ __forceinline__ void hg_passB(const Ptrs& P, int l, int b, int hd, int ch, unsigned char* lds, int tid, bool dost) {
;     ...
; #pragma unroll
;     for (int j = 0; j < 8; ++j) { float part = (oo[j][0] * oo[j][0] + oo[j][1] * oo[j][1]) + (oo[j][2] * oo[j][2] + oo[j][3] * oo[j][3]);
;         part += shx(part, 16, lane); part += shx(part, 32, lane); if (g == 0) SSQ[w * 128 + 16 * j + lc] = part; }
.LBB0_857:
	s_or_b64 exec, exec, s[4:5]
	s_waitcnt lgkmcnt(0)
	v_mul_f32_e32 v52, v47, v47
	v_mul_f32_e32 v77, v49, v49
	v_fmac_f32_e32 v52, v46, v46
	v_fmac_f32_e32 v77, v48, v48
	v_add_f32_e32 v52, v52, v77
	v_mul_f32_e32 v53, v43, v43
	v_mul_f32_e32 v77, v45, v45
	v_fmac_f32_e32 v53, v42, v42
	v_fmac_f32_e32 v77, v44, v44
	v_add_f32_e32 v53, v53, v77
	v_mul_f32_e32 v54, v39, v39
	v_mul_f32_e32 v77, v41, v41
	v_fmac_f32_e32 v54, v38, v38
	v_fmac_f32_e32 v77, v40, v40
	v_add_f32_e32 v54, v54, v77
	v_mul_f32_e32 v55, v27, v27
	v_mul_f32_e32 v77, v29, v29
	v_fmac_f32_e32 v55, v26, v26
	v_fmac_f32_e32 v77, v28, v28
	v_add_f32_e32 v55, v55, v77
	v_mul_f32_e32 v56, v23, v23
	v_mul_f32_e32 v77, v25, v25
	v_fmac_f32_e32 v56, v22, v22
	v_fmac_f32_e32 v77, v24, v24
	v_add_f32_e32 v56, v56, v77
	v_mul_f32_e32 v57, v19, v19
	v_mul_f32_e32 v77, v21, v21
	v_fmac_f32_e32 v57, v18, v18
	v_fmac_f32_e32 v77, v20, v20
	v_add_f32_e32 v57, v57, v77
	v_mul_f32_e32 v58, v9, v9
	v_mul_f32_e32 v77, v11, v11
	v_fmac_f32_e32 v58, v8, v8
	v_fmac_f32_e32 v77, v10, v10
	v_add_f32_e32 v58, v58, v77
	ds_bpermute_b32 v59, v50, v52
	ds_bpermute_b32 v60, v50, v53
	ds_bpermute_b32 v62, v50, v54
	ds_bpermute_b32 v70, v50, v55
	ds_bpermute_b32 v72, v50, v56
	ds_bpermute_b32 v73, v50, v57
	ds_bpermute_b32 v76, v50, v58
	s_waitcnt lgkmcnt(6)
	v_add_f32_e32 v52, v52, v59
	s_waitcnt lgkmcnt(5)
	v_add_f32_e32 v53, v53, v60
	s_waitcnt lgkmcnt(4)
	v_add_f32_e32 v54, v54, v62
	s_waitcnt lgkmcnt(3)
	v_add_f32_e32 v55, v55, v70
	s_waitcnt lgkmcnt(2)
	v_add_f32_e32 v56, v56, v72
	s_waitcnt lgkmcnt(1)
	v_add_f32_e32 v57, v57, v73
	s_waitcnt lgkmcnt(0)
	v_add_f32_e32 v58, v58, v76
	s_nop 1
	ds_bpermute_b32 v59, v51, v52
	ds_bpermute_b32 v60, v51, v53
	ds_bpermute_b32 v62, v51, v54
	ds_bpermute_b32 v70, v51, v55
	ds_bpermute_b32 v72, v51, v56
	ds_bpermute_b32 v73, v51, v57
	ds_bpermute_b32 v76, v51, v58
	s_and_saveexec_b64 s[4:5], vcc
	s_cbranch_execz .LBB0_871
	s_waitcnt lgkmcnt(6)
	v_add_f32_e32 v52, v52, v59
	s_waitcnt lgkmcnt(5)
	v_add_f32_e32 v53, v53, v60
	s_waitcnt lgkmcnt(4)
	v_add_f32_e32 v54, v54, v62
	s_waitcnt lgkmcnt(3)
	v_add_f32_e32 v55, v55, v70
	s_waitcnt lgkmcnt(2)
	v_add_f32_e32 v56, v56, v72
	s_waitcnt lgkmcnt(1)
	v_add_f32_e32 v57, v57, v73
	s_waitcnt lgkmcnt(0)
	v_add_f32_e32 v58, v58, v76
	ds_write_b32 v12, v52 offset:64
	ds_write_b32 v12, v53 offset:128
	ds_write_b32 v12, v54 offset:192
	ds_write_b32 v12, v55 offset:256
	ds_write_b32 v12, v56 offset:320
	ds_write_b32 v12, v57 offset:384
	ds_write_b32 v12, v58 offset:448
